# NA tile loop: 16 exec-masked bias LDS reads issued unconditionally together, one wait, v_cndmask -inf select (was 16 serialized LDS round trips)
# speedup vs baseline: 1.0376x; 1.0086x over previous
; #define LAS __attribute__((address_space(3)))
; template <bool NA> ...
;     ...
;         if (NA && j >= 4) { kr = na_rs_base + (j - 4); active = (kr >= na_rs) && (kr < na_rs + 8); }
;         if (active) {
;             const LAS unsigned char* kb = lds + cur * KB; const LAS unsigned char* vb = lds + VOFF + cur * VB;
;             f32x16 p0, p1;
;             if (NA) {
; #pragma unroll
;                 for (int r = 0; r < 16; ++r) { p0[r] = 0.f; p1[r] = 0.f; }
;             } else { p0 = negm; p1 = negm; }
;             bf16x8 kf[8], vfr[8];
; #pragma unroll
;             for (int s = 0; s < 4; ++s) {
;                 kf[2 * s] = *(const LAS bf16x8*)(kb + q * 144 + (16 * s + 8 * h) * 2);
;                 kf[2 * s + 1] = *(const LAS bf16x8*)(kb + (q + 32) * 144 + (16 * s + 8 * h) * 2);
;             }
; #pragma unroll
;             for (int s = 0; s < 4; ++s) {
;                 vfr[2 * s] = *(const LAS bf16x8*)(vb + q * 144 + 32 * s + 16 * h);
;                 vfr[2 * s + 1] = *(const LAS bf16x8*)(vb + (q + 32) * 144 + 32 * s + 16 * h);
;             }
;             __builtin_amdgcn_sched_barrier(0);
;             __builtin_amdgcn_s_setprio(1);
; #pragma unroll
;             for (int s = 0; s < 4; ++s) {
;                 p0 = __builtin_amdgcn_mfma_f32_32x32x16_bf16(kf[2 * s], qb[s], p0, 0, 0, 0);
;                 p1 = __builtin_amdgcn_mfma_f32_32x32x16_bf16(kf[2 * s + 1], qb[s], p1, 0, 0, 0);
;             }
;             __builtin_amdgcn_s_setprio(0);
;             if (NA) {
;                 if (j >= 4) {
;                     const int dr = kr - na_r + 7, qc = na_qc0 + q;
; #pragma unroll
;                     for (int r = 0; r < 16; ++r) {
;                         const int kc = 8 * (r >> 2) + 4 * h + (r & 3);
;                         const bool v0 = (kc >= na_cs) && (kc < na_cs + 16), v1 = (kc + 32 >= na_cs) && (kc + 32 < na_cs + 16);
;                         const int i0 = v0 ? dr * 31 + (kc - qc + 15) : 0, i1 = v1 ? dr * 31 + (kc + 32 - qc + 15) : 0;
;                         const float b0 = biasL[i0], b1 = biasL[i1];
;                         p0[r] = v0 ? p0[r] * qs + b0 - m : -INFINITY; p1[r] = v1 ? p1[r] * qs + b1 - m : -INFINITY;
.LBB0_390:
	s_and_b32 s29, s33, 1
	s_cmp_gt_u32 s33, 3
	s_cselect_b64 s[72:73], -1, 0
	s_cmp_lt_u32 s33, 4
	s_cselect_b64 s[36:37], -1, 0
	s_add_i32 s33, s27, s25
	s_add_i32 s33, s33, 8
	s_cmp_ge_i32 s33, s2
	s_cselect_b64 s[46:47], -1, 0
	s_cmp_lt_i32 s33, s20
	s_cselect_b64 s[48:49], -1, 0
	s_and_b64 s[46:47], s[46:47], s[48:49]
	s_or_b64 s[36:37], s[36:37], s[46:47]
	s_andn2_b64 vcc, exec, s[36:37]
	s_cbranch_vccnz .LBB0_430
	s_mul_i32 s33, s29, 0x2400
	v_add_u32_e32 v0, s33, v217
	ds_read_b128 v[48:51], v0
	ds_read_b128 v[52:55], v0 offset:32
	ds_read_b128 v[56:59], v0 offset:4608
	ds_read_b128 v[60:63], v0 offset:4640
	ds_read_b128 v[64:67], v0 offset:64
	ds_read_b128 v[68:71], v0 offset:96
	ds_read_b128 v[72:75], v0 offset:4672
	ds_read_b128 v[76:79], v0 offset:4704
	ds_read_b128 v[152:155], v0 offset:18432
	ds_read_b128 v[140:143], v0 offset:18464
	ds_read_b128 v[148:151], v0 offset:23040
	ds_read_b128 v[144:147], v0 offset:23072
	ds_read_b128 v[10:13], v0 offset:18496
	ds_read_b128 v[6:9], v0 offset:18528
	ds_read_b128 v[136:139], v0 offset:23104
	ds_read_b128 v[2:5], v0 offset:23136
	s_setprio 1
	s_waitcnt lgkmcnt(14)
	v_mfma_f32_32x32x16_bf16 v[96:111], v[48:51], v[120:123], 0
	s_waitcnt lgkmcnt(13)
	v_mfma_f32_32x32x16_bf16 v[80:95], v[56:59], v[120:123], 0
	v_mfma_f32_32x32x16_bf16 v[96:111], v[52:55], v[112:115], v[96:111]
	s_waitcnt lgkmcnt(12)
	v_mfma_f32_32x32x16_bf16 v[80:95], v[60:63], v[112:115], v[80:95]
	s_waitcnt lgkmcnt(11)
	v_mfma_f32_32x32x16_bf16 v[96:111], v[64:67], v[116:119], v[96:111]
	s_waitcnt lgkmcnt(9)
	v_mfma_f32_32x32x16_bf16 v[80:95], v[72:75], v[116:119], v[80:95]
	v_mfma_f32_32x32x16_bf16 v[96:111], v[68:71], v[124:127], v[96:111]
	s_waitcnt lgkmcnt(8)
	v_mfma_f32_32x32x16_bf16 v[80:95], v[76:79], v[124:127], v[80:95]
	s_setprio 0
	s_mov_b64 s[46:47], -1
	s_and_b64 vcc, exec, s[72:73]
	s_cbranch_vccz .LBB0_425
	v_subrev_u32_e32 v0, 27, v197
	v_cndmask_b32_e64 v0, 0, v0, s[50:51]
	v_lshl_add_u32 v0, v0, 2, 0
	ds_read_b32 v0, v0 offset:36864
	ds_read_b32 v48, v15
.LBB0_394:
	v_subrev_u32_e32 v50, 26, v197
	v_cndmask_b32_e64 v50, 0, v50, s[54:55]
	v_lshl_add_u32 v50, v50, 2, 0
	ds_read_b32 v65, v50 offset:36864
	ds_read_b32 v49, v15 offset:4
.LBB0_396:
	v_subrev_u32_e32 v50, 25, v197
	v_cndmask_b32_e64 v50, 0, v50, s[58:59]
	v_lshl_add_u32 v50, v50, 2, 0
	ds_read_b32 v66, v50 offset:36864
	ds_read_b32 v50, v15 offset:8
.LBB0_398:
	v_subrev_u32_e32 v52, 24, v197
	v_cndmask_b32_e64 v52, 0, v52, s[62:63]
	v_lshl_add_u32 v52, v52, 2, 0
	ds_read_b32 v67, v52 offset:36864
	ds_read_b32 v51, v15 offset:12
.LBB0_400:
	v_subrev_u32_e32 v52, 19, v197
	v_cndmask_b32_e64 v52, 0, v52, s[66:67]
	v_lshl_add_u32 v52, v52, 2, 0
	ds_read_b32 v68, v52 offset:36864
	ds_read_b32 v52, v15 offset:32
.LBB0_402:
	v_subrev_u32_e32 v54, 18, v197
	v_cndmask_b32_e64 v54, 0, v54, s[70:71]
	v_lshl_add_u32 v54, v54, 2, 0
	ds_read_b32 v69, v54 offset:36864
	ds_read_b32 v53, v15 offset:36
.LBB0_404:
	v_subrev_u32_e32 v54, 17, v197
	v_cndmask_b32_e64 v54, 0, v54, s[74:75]
	v_lshl_add_u32 v54, v54, 2, 0
	ds_read_b32 v70, v54 offset:36864
	ds_read_b32 v54, v15 offset:40
.LBB0_406:
	v_add_u32_e32 v56, -16, v197
	v_cndmask_b32_e64 v56, 0, v56, s[78:79]
	v_lshl_add_u32 v56, v56, 2, 0
	ds_read_b32 v71, v56 offset:36864
	ds_read_b32 v55, v15 offset:44
.LBB0_408:
	v_add_u32_e32 v56, -11, v197
	v_cndmask_b32_e64 v56, 0, v56, s[80:81]
	v_lshl_add_u32 v56, v56, 2, 0
	ds_read_b32 v72, v56 offset:36864
	ds_read_b32 v56, v15 offset:64
.LBB0_410:
	v_add_u32_e32 v58, -10, v197
	v_cndmask_b32_e64 v58, 0, v58, s[82:83]
	v_lshl_add_u32 v58, v58, 2, 0
	ds_read_b32 v73, v58 offset:36864
	ds_read_b32 v57, v15 offset:68
.LBB0_412:
	v_add_u32_e32 v58, -9, v197
	v_cndmask_b32_e64 v58, 0, v58, s[84:85]
	v_lshl_add_u32 v58, v58, 2, 0
	ds_read_b32 v74, v58 offset:36864
	ds_read_b32 v58, v15 offset:72
.LBB0_414:
	v_add_u32_e32 v60, -8, v197
	v_cndmask_b32_e64 v60, 0, v60, s[86:87]
	v_lshl_add_u32 v60, v60, 2, 0
	ds_read_b32 v75, v60 offset:36864
	ds_read_b32 v59, v15 offset:76
.LBB0_416:
	v_add_u32_e32 v60, -3, v197
	v_cndmask_b32_e64 v60, 0, v60, s[88:89]
	v_lshl_add_u32 v60, v60, 2, 0
	ds_read_b32 v76, v60 offset:36864
	ds_read_b32 v60, v15 offset:96
.LBB0_418:
	v_add_u32_e32 v62, -2, v197
	v_cndmask_b32_e64 v62, 0, v62, s[90:91]
	v_lshl_add_u32 v62, v62, 2, 0
	ds_read_b32 v77, v62 offset:36864
	ds_read_b32 v61, v15 offset:100
.LBB0_420:
	v_add_u32_e32 v62, -1, v197
	v_cndmask_b32_e64 v62, 0, v62, s[92:93]
	v_lshl_add_u32 v62, v62, 2, 0
	ds_read_b32 v78, v62 offset:36864
	ds_read_b32 v62, v15 offset:104
; template <bool NA> ...
;     ...
;                 if (j >= 4) {
;                     const int dr = kr - na_r + 7, qc = na_qc0 + q;
; #pragma unroll
;                     for (int r = 0; r < 16; ++r) {
;                         const int kc = 8 * (r >> 2) + 4 * h + (r & 3);
;                         const bool v0 = (kc >= na_cs) && (kc < na_cs + 16), v1 = (kc + 32 >= na_cs) && (kc + 32 < na_cs + 16);
;                         const int i0 = v0 ? dr * 31 + (kc - qc + 15) : 0, i1 = v1 ? dr * 31 + (kc + 32 - qc + 15) : 0;
;                         const float b0 = biasL[i0], b1 = biasL[i1];
;                         p0[r] = v0 ? p0[r] * qs + b0 - m : -INFINITY; p1[r] = v1 ? p1[r] * qs + b1 - m : -INFINITY;
;                     }
.LBB0_422:
	v_cndmask_b32_e64 v64, 0, v197, s[94:95]
	v_lshl_add_u32 v64, v64, 2, 0
	ds_read_b32 v79, v64 offset:36864
	ds_read_b32 v63, v15 offset:108
.LBB0_424:
	s_waitcnt lgkmcnt(0)
	v_readlane_b32 s8, v253, 29
	v_readlane_b32 s9, v253, 30
	v_fmac_f32_e32 v48, 0x3e38aa3b, v96
	v_sub_f32_e32 v48, v48, v14
	v_cndmask_b32_e64 v48, v208, v48, s[8:9]
	v_readlane_b32 s8, v253, 35
	v_readlane_b32 s9, v253, 36
	v_fmac_f32_e32 v49, 0x3e38aa3b, v97
	v_sub_f32_e32 v49, v49, v14
	v_cndmask_b32_e64 v49, v208, v49, s[8:9]
	v_readlane_b32 s8, v253, 37
	v_readlane_b32 s9, v253, 38
	v_fmac_f32_e32 v50, 0x3e38aa3b, v98
	v_sub_f32_e32 v50, v50, v14
	v_cndmask_b32_e64 v50, v208, v50, s[8:9]
	v_readlane_b32 s8, v253, 39
	v_readlane_b32 s9, v253, 40
	v_fmac_f32_e32 v51, 0x3e38aa3b, v99
	v_sub_f32_e32 v51, v51, v14
	v_cndmask_b32_e64 v51, v208, v51, s[8:9]
	v_readlane_b32 s8, v253, 41
	v_readlane_b32 s9, v253, 42
	v_fmac_f32_e32 v52, 0x3e38aa3b, v100
	v_sub_f32_e32 v52, v52, v14
	v_cndmask_b32_e64 v52, v208, v52, s[8:9]
	v_readlane_b32 s8, v253, 43
	v_readlane_b32 s9, v253, 44
	v_fmac_f32_e32 v53, 0x3e38aa3b, v101
	v_sub_f32_e32 v53, v53, v14
	v_cndmask_b32_e64 v53, v208, v53, s[8:9]
	v_readlane_b32 s8, v253, 45
	v_readlane_b32 s9, v253, 46
	v_fmac_f32_e32 v54, 0x3e38aa3b, v102
	v_sub_f32_e32 v54, v54, v14
	v_cndmask_b32_e64 v54, v208, v54, s[8:9]
	v_readlane_b32 s8, v253, 47
	v_readlane_b32 s9, v253, 48
	v_fmac_f32_e32 v55, 0x3e38aa3b, v103
	v_sub_f32_e32 v55, v55, v14
	v_cndmask_b32_e64 v55, v208, v55, s[8:9]
	v_readlane_b32 s8, v253, 49
	v_readlane_b32 s9, v253, 50
	v_fmac_f32_e32 v56, 0x3e38aa3b, v104
	v_sub_f32_e32 v56, v56, v14
	v_cndmask_b32_e64 v56, v208, v56, s[8:9]
	v_readlane_b32 s8, v253, 51
	v_readlane_b32 s9, v253, 52
	v_fmac_f32_e32 v57, 0x3e38aa3b, v105
	v_sub_f32_e32 v57, v57, v14
	v_cndmask_b32_e64 v57, v208, v57, s[8:9]
	v_readlane_b32 s8, v253, 53
	v_readlane_b32 s9, v253, 54
	v_fmac_f32_e32 v58, 0x3e38aa3b, v106
	v_sub_f32_e32 v58, v58, v14
	v_cndmask_b32_e64 v58, v208, v58, s[8:9]
	v_readlane_b32 s8, v253, 55
	v_readlane_b32 s9, v253, 56
	v_fmac_f32_e32 v59, 0x3e38aa3b, v107
	v_sub_f32_e32 v59, v59, v14
	v_cndmask_b32_e64 v59, v208, v59, s[8:9]
	v_fmac_f32_e32 v60, 0x3e38aa3b, v108
	v_sub_f32_e32 v60, v60, v14
	v_cndmask_b32_e64 v60, v208, v60, s[44:45]
	v_fmac_f32_e32 v61, 0x3e38aa3b, v109
	v_sub_f32_e32 v61, v61, v14
	v_cndmask_b32_e64 v61, v208, v61, s[64:65]
	v_fmac_f32_e32 v62, 0x3e38aa3b, v110
	v_sub_f32_e32 v62, v62, v14
	v_cndmask_b32_e64 v62, v208, v62, s[68:69]
	v_fmac_f32_e32 v63, 0x3e38aa3b, v111
	v_sub_f32_e32 v63, v63, v14
	v_cndmask_b32_e64 v63, v208, v63, s[4:5]
	s_waitcnt lgkmcnt(14)
	v_fmac_f32_e32 v0, 0x3e38aa3b, v80
	v_sub_f32_e32 v0, v0, v14
	v_fmac_f32_e32 v65, 0x3e38aa3b, v81
	v_cndmask_b32_e64 v64, v208, v0, s[50:51]
	v_sub_f32_e32 v0, v65, v14
	s_waitcnt lgkmcnt(13)
	v_fmac_f32_e32 v66, 0x3e38aa3b, v82
	v_cndmask_b32_e64 v65, v208, v0, s[54:55]
	v_sub_f32_e32 v0, v66, v14
	s_waitcnt lgkmcnt(12)
	v_fmac_f32_e32 v67, 0x3e38aa3b, v83
	v_cndmask_b32_e64 v66, v208, v0, s[58:59]
	v_sub_f32_e32 v0, v67, v14
	s_waitcnt lgkmcnt(11)
	v_fmac_f32_e32 v68, 0x3e38aa3b, v84
	v_cndmask_b32_e64 v67, v208, v0, s[62:63]
	v_sub_f32_e32 v0, v68, v14
	s_waitcnt lgkmcnt(10)
	v_fmac_f32_e32 v69, 0x3e38aa3b, v85
	v_cndmask_b32_e64 v68, v208, v0, s[66:67]
	v_sub_f32_e32 v0, v69, v14
	s_waitcnt lgkmcnt(9)
	v_fmac_f32_e32 v70, 0x3e38aa3b, v86
	v_cndmask_b32_e64 v69, v208, v0, s[70:71]
	v_sub_f32_e32 v0, v70, v14
	s_waitcnt lgkmcnt(8)
	v_fmac_f32_e32 v71, 0x3e38aa3b, v87
	v_cndmask_b32_e64 v70, v208, v0, s[74:75]
	v_sub_f32_e32 v0, v71, v14
	s_waitcnt lgkmcnt(7)
	v_fmac_f32_e32 v72, 0x3e38aa3b, v88
	v_cndmask_b32_e64 v71, v208, v0, s[78:79]
	v_sub_f32_e32 v0, v72, v14
	s_waitcnt lgkmcnt(6)
	v_fmac_f32_e32 v73, 0x3e38aa3b, v89
	v_cndmask_b32_e64 v72, v208, v0, s[80:81]
	v_sub_f32_e32 v0, v73, v14
	s_waitcnt lgkmcnt(5)
	v_fmac_f32_e32 v74, 0x3e38aa3b, v90
	v_cndmask_b32_e64 v73, v208, v0, s[82:83]
	v_sub_f32_e32 v0, v74, v14
	s_waitcnt lgkmcnt(4)
	v_fmac_f32_e32 v75, 0x3e38aa3b, v91
	v_cndmask_b32_e64 v74, v208, v0, s[84:85]
	v_sub_f32_e32 v0, v75, v14
	s_waitcnt lgkmcnt(3)
	v_fmac_f32_e32 v76, 0x3e38aa3b, v92
	v_cndmask_b32_e64 v75, v208, v0, s[86:87]
	v_sub_f32_e32 v0, v76, v14
	s_waitcnt lgkmcnt(2)
	v_fmac_f32_e32 v77, 0x3e38aa3b, v93
	v_cndmask_b32_e64 v76, v208, v0, s[88:89]
	v_sub_f32_e32 v0, v77, v14
	s_waitcnt lgkmcnt(1)
	v_fmac_f32_e32 v78, 0x3e38aa3b, v94
	v_cndmask_b32_e64 v77, v208, v0, s[90:91]
	v_sub_f32_e32 v0, v78, v14
	s_waitcnt lgkmcnt(0)
	v_fmac_f32_e32 v79, 0x3e38aa3b, v95
	v_cndmask_b32_e64 v78, v208, v0, s[92:93]
	v_sub_f32_e32 v0, v79, v14
	v_cndmask_b32_e64 v79, v208, v0, s[94:95]
	s_mov_b64 s[46:47], 0
